# in-proj GEMM: the ragged last round (48 tiles) is split into N-halves over 96 workgroups; each computes and stores only its half of the accumulators
# speedup vs baseline: 1.0026x; 1.0026x over previous
.LBB0_664:
	s_and_b64 vcc, exec, s[2:3]
	s_cbranch_vccz .LBB0_677
	s_cmpk_gt_i32 s0, 0x62f
	v_readfirstlane_b32 s1, v158
	s_cbranch_scc1 .LBB0_677
	s_mov_b32 s101, 0
	v_lshlrev_b32_e32 v0, 4, v158
	s_waitcnt vmcnt(0)
	v_add_u32_e32 v2, 0x2000, v0
	v_ashrrev_i32_e32 v3, 31, v2
	v_lshrrev_b32_e32 v3, 22, v3
	v_add_u32_e32 v3, v2, v3
	v_ashrrev_i32_e32 v10, 10, v3
	v_mul_i32_i24_e32 v3, 0x400, v10
	v_sub_u32_e32 v2, v2, v3
	v_lshrrev_b32_e32 v3, 4, v2
	v_bitop3_b32 v2, v3, v2, 32 bitop3:0x6c
	s_load_dwordx2 s[2:3], s[54:55], 0x108
	v_ashrrev_i32_e32 v3, 31, v2
	v_lshrrev_b32_e32 v3, 26, v3
	v_add_u32_e32 v3, v2, v3
	v_lshlrev_b32_e32 v4, 3, v10
	s_mov_b32 s10, s44
	v_ashrrev_i32_e32 v11, 6, v3
	v_and_b32_e32 v4, -16, v4
	s_mul_i32 s9, s10, 0x600000
	v_add_u32_e32 v4, v11, v4
	s_load_dwordx4 s[44:47], s[54:55], 0x158
	s_waitcnt lgkmcnt(0)
	s_add_u32 s26, s2, s9
	v_and_b32_e32 v5, 3, v11
	s_mov_b32 s2, 0x1fffe0
	v_lshrrev_b32_e32 v6, 2, v4
	v_lshlrev_b32_e32 v7, 1, v4
	v_and_b32_e32 v3, 0xc0, v3
	v_and_or_b32 v5, v4, s2, v5
	v_and_b32_e32 v6, 4, v6
	v_and_b32_e32 v7, 24, v7
	v_sub_u32_e32 v2, v2, v3
	v_or3_b32 v5, v5, v6, v7
	v_lshlrev_b32_e32 v6, 5, v10
	v_ashrrev_i16_sdwa v2, v207, sext(v2) dst_sel:DWORD dst_unused:UNUSED_PAD src0_sel:DWORD src1_sel:BYTE_0
	v_and_b32_e32 v6, 32, v6
	v_bfe_i32 v12, v2, 0, 16
	v_add_lshl_u32 v2, v6, v12, 1
	v_lshl_add_u32 v130, v5, 11, v2
	v_lshl_add_u32 v132, v4, 11, v2
	v_bfe_i32 v2, v158, 27, 1
	v_lshrrev_b32_e32 v2, 22, v2
	v_add_u32_e32 v2, v0, v2
	v_and_b32_e32 v2, 0xfffffc00, v2
	v_sub_u32_e32 v0, v0, v2
	v_lshrrev_b32_e32 v2, 4, v0
	v_bitop3_b32 v2, v2, v0, 32 bitop3:0x6c
	v_ashrrev_i32_e32 v0, 31, v0
	v_lshrrev_b32_e32 v0, 26, v0
	v_add_u32_e32 v0, v2, v0
	v_ashrrev_i32_e32 v13, 6, v0
	v_ashrrev_i32_e32 v0, 31, v158
	v_lshrrev_b32_e32 v0, 26, v0
	v_add_u32_e32 v0, v158, v0
	v_ashrrev_i32_e32 v14, 6, v0
	v_lshlrev_b32_e32 v0, 3, v14
	s_mul_hi_i32 s8, s10, 0x600000
	v_and_b32_e32 v0, -16, v0
	s_addc_u32 s27, s3, s8
	v_add_u32_e32 v3, v13, v0
	v_and_b32_e32 v0, 3, v13
	s_ashr_i32 s29, s0, 31
	v_and_or_b32 v0, v3, s2, v0
	s_lshr_b32 s2, s29, 29
	s_add_i32 s2, s0, s2
	s_ashr_i32 s10, s1, 6
	s_ashr_i32 s3, s2, 3
	s_and_b32 s2, s2, -8
	s_ashr_i32 s9, s1, 8
	s_lshl_b32 s28, s10, 10
	s_sub_i32 s2, s0, s2
	s_mov_b32 s59, s57
	s_cmp_lt_i32 s2, 0
	s_movk_i32 s57, 0xc7
	s_cselect_b32 s8, s57, 0xc6
	s_mul_i32 s2, s8, s2
	s_add_i32 s2, s2, s3
	s_mul_hi_i32 s3, s2, 0x2aaaaaab
	v_lshrrev_b32_e32 v4, 2, v3
	v_lshlrev_b32_e32 v5, 1, v3
	s_lshr_b32 s8, s3, 31
	s_ashr_i32 s3, s3, 4
	v_and_b32_e32 v4, 4, v4
	v_and_b32_e32 v5, 24, v5
	s_add_i32 s3, s3, s8
	v_or3_b32 v0, v0, v4, v5
	v_mul_i32_i24_e32 v5, 64, v13
	s_lshl_b32 s11, s3, 3
	v_sub_u32_e32 v2, v2, v5
	s_sub_i32 s8, 0x84, s11
	v_lshlrev_b32_e32 v4, 5, v14
	v_ashrrev_i16_sdwa v2, v207, sext(v2) dst_sel:DWORD dst_unused:UNUSED_PAD src0_sel:DWORD src1_sel:BYTE_0
	s_min_u32 s12, s8, 8
	s_mulk_i32 s3, 0x60
	v_and_b32_e32 v4, 32, v4
	v_bfe_i32 v15, v2, 0, 16
	s_sub_i32 s13, s2, s3
	v_cvt_f32_ubyte0_e32 v5, s12
	v_add_lshl_u32 v2, v4, v15, 1
	v_cvt_f32_i32_e32 v4, s13
	v_rcp_iflag_f32_e32 v6, v5
	v_lshl_add_u32 v0, v0, 11, v2
	v_lshl_add_u32 v134, v3, 11, v2
	s_ashr_i32 s2, s13, 30
	v_mul_f32_e32 v2, v4, v6
	v_trunc_f32_e32 v2, v2
	v_fma_f32 v3, -v2, v5, v4
	v_cvt_i32_f32_e32 v2, v2
	s_or_b32 s8, s2, 1
	v_cmp_ge_f32_e64 s[2:3], |v3|, v5
	s_and_b64 s[2:3], s[2:3], exec
	s_cselect_b32 s2, s8, 0
	v_readfirstlane_b32 s3, v2
	s_add_i32 s8, s3, s2
	s_mul_i32 s2, s8, s12
	s_sub_i32 s2, s13, s2
	s_sext_i32_i8 s2, s2
	s_add_i32 s2, s11, s2
	s_ashr_i32 s3, s2, 31
	s_bfe_i64 s[14:15], s[8:9], 0x80000
	s_lshl_b64 s[12:13], s[2:3], 19
	s_lshl_b64 s[14:15], s[14:15], 19
	s_add_u32 s18, s26, s14
	s_addc_u32 s19, s27, s15
	s_add_i32 s3, s28, 0
	s_add_i32 m0, s3, 0x10000
	v_mov_b32_e32 v131, v1
	global_load_lds_dwordx4 v0, s[18:19]
	s_add_i32 m0, s3, 0x12000
	s_add_u32 s22, s44, s12
	global_load_lds_dwordx4 v130, s[18:19]
	s_addc_u32 s23, s45, s13
	s_mov_b32 m0, s3
	s_add_i32 s30, s3, 0x2000
	global_load_lds_dwordx4 v134, s[22:23]
	s_mov_b32 m0, s30
	s_add_u32 s12, s18, 0x40000
	global_load_lds_dwordx4 v132, s[22:23]
	s_addc_u32 s13, s19, 0
	s_add_i32 m0, s3, 0x14000
	v_mov_b32_e32 v135, v1
	global_load_lds_dwordx4 v0, s[12:13]
	s_add_i32 m0, s3, 0x16000
	v_mov_b32_e32 v133, v1
	global_load_lds_dwordx4 v130, s[12:13]
	s_add_u32 s12, s22, 0x40000
	s_addc_u32 s13, s23, 0
	s_add_i32 s31, s3, 0x4000
	s_mov_b32 m0, s31
	s_add_i32 s34, s3, 0x6000
	global_load_lds_dwordx4 v134, s[12:13]
	s_mov_b32 m0, s34
	s_mov_b32 s60, s56
	global_load_lds_dwordx4 v132, s[12:13]
	v_lshl_add_u64 v[8:9], s[18:19], 0, v[0:1]
	v_lshl_add_u64 v[6:7], s[18:19], 0, v[130:131]
	v_lshl_add_u64 v[4:5], s[22:23], 0, v[134:135]
	s_cmp_lg_u32 s9, 1
	v_lshl_add_u64 v[2:3], s[22:23], 0, v[132:133]
	s_cbranch_scc1 .LBB0_668
	s_barrier

.LBB0_669:
	s_mov_b32 s100, s101
	s_mov_b32 s101, 0
	s_add_i32 s42, s42, 1
	s_mul_i32 s9, s42, s39
	s_mul_hi_u32 s11, s42, s60
	s_add_i32 s11, s11, s9
	s_mul_i32 s9, s42, s60
	s_add_u32 s12, s9, s0
	s_addc_u32 s13, s11, s29
	s_cmp_lg_u32 s42, 6
	s_cbranch_scc1 .Lht_ip_done
	s_cmp_lg_u32 s60, 0x100
	s_cbranch_scc1 .Lht_ip_done
	s_mov_b32 s12, 0x630
	s_mov_b32 s13, 0
	s_cmp_gt_u32 s0, 95
	s_cbranch_scc1 .Lht_ip_done
	s_mov_b32 s101, 1
	s_mov_b32 s12, s0
	s_cmp_lt_u32 s0, 48
	s_cbranch_scc1 .Lht_ip_add
	s_mov_b32 s101, 2
	s_sub_u32 s12, s0, 48
.Lht_ip_add:
	s_add_u32 s12, s12, 0x600
.Lht_ip_done:
	v_cmp_gt_i64_e64 s[40:41], s[12:13], v[154:155]
	s_and_b64 vcc, exec, s[40:41]
	s_cbranch_vccnz .LBB0_671
	s_ashr_i32 s8, s12, 31
	s_lshr_b32 s8, s8, 29
	s_add_i32 s8, s12, s8
	s_ashr_i32 s9, s8, 3
	s_and_b32 s8, s8, -8
	s_sub_i32 s8, s12, s8
	s_cmp_lt_i32 s8, 0
	s_cselect_b32 s10, s57, 0xc6
	s_mul_i32 s8, s10, s8
	s_add_i32 s8, s8, s9
	s_mul_hi_i32 s9, s8, 0x2aaaaaab
	s_lshr_b32 s10, s9, 31
	s_ashr_i32 s9, s9, 4
	s_add_i32 s9, s9, s10
	s_lshl_b32 s10, s9, 3
	s_sub_i32 s11, 0x84, s10
	s_min_i32 s11, s11, 8
	s_abs_i32 s14, s11
	v_cvt_f32_u32_e32 v2, s14
	s_sub_i32 s24, 0, s14
	s_mulk_i32 s9, 0x60
	s_sub_i32 s9, s8, s9
	v_rcp_iflag_f32_e32 v2, v2
	s_abs_i32 s8, s9
	s_xor_b32 s15, s9, s11
	s_ashr_i32 s15, s15, 31
	v_mul_f32_e32 v2, 0x4f7ffffe, v2
	v_cvt_u32_f32_e32 v2, v2
	s_nop 0
	v_readfirstlane_b32 s25, v2
	s_mul_i32 s24, s24, s25
	s_mul_hi_u32 s24, s25, s24
	s_add_i32 s25, s25, s24
	s_mul_hi_u32 s24, s8, s25
	s_mul_i32 s25, s24, s14
	s_sub_i32 s8, s8, s25
	s_add_i32 s48, s24, 1
	s_sub_i32 s25, s8, s14
	s_cmp_ge_u32 s8, s14
	s_cselect_b32 s24, s48, s24
	s_cselect_b32 s8, s25, s8
	s_add_i32 s25, s24, 1
	s_cmp_ge_u32 s8, s14
	s_cselect_b32 s8, s25, s24
	s_xor_b32 s8, s8, s15
	s_sub_i32 s8, s8, s15
	s_mul_i32 s11, s8, s11
	s_sub_i32 s9, s9, s11
	s_add_i32 s10, s9, s10

.LBB0_672:
	s_add_u32 s22, s18, 0xfffc0080
	s_addc_u32 s23, s19, -1
	s_add_i32 s53, 0, 0x10000
	v_add_u32_e32 v148, s53, v141
	ds_read_b128 v[144:147], v148
	ds_read_b128 v[160:163], v148 offset:1024
	ds_read_b128 v[164:167], v148 offset:2048
	ds_read_b128 v[168:171], v148 offset:3072
	s_cmp_eq_u32 s52, 12
	s_cselect_b32 s25, s11, s23
	s_cselect_b32 s24, s48, s22
	s_cselect_b32 s23, s9, s51
	s_cselect_b32 s22, s49, s50
	v_lshl_add_u64 v[148:149], s[18:19], 0, v[138:139]
	s_add_i32 m0, s3, 0xc000
	ds_read_b128 v[172:175], v143
	ds_read_b128 v[176:179], v143 offset:1024
	ds_read_b128 v[180:183], v143 offset:2048
	ds_read_b128 v[184:187], v143 offset:3072
	ds_read_b128 v[188:191], v143 offset:4096
	ds_read_b128 v[192:195], v143 offset:5120
	ds_read_b128 v[196:199], v143 offset:6144
	ds_read_b128 v[200:203], v143 offset:7168
	global_load_lds_dwordx4 v[148:149], off
	v_lshl_add_u64 v[148:149], s[18:19], 0, v[136:137]
	s_add_i32 m0, s3, 0xe000
	s_nop 0
	global_load_lds_dwordx4 v[148:149], off
	s_waitcnt lgkmcnt(8)
	s_barrier
	s_waitcnt lgkmcnt(0)
	s_setprio 1
	s_waitcnt lgkmcnt(0)
	s_cmp_eq_u32 s100, 2
	s_cbranch_scc1 .Lht_ip_mf0
	v_mfma_f32_16x16x32_bf16 v[126:129], v[144:147], v[172:175], v[126:129]
	v_mfma_f32_16x16x32_bf16 v[122:125], v[164:167], v[172:175], v[122:125]
	v_mfma_f32_16x16x32_bf16 v[118:121], v[144:147], v[180:183], v[118:121]
	v_mfma_f32_16x16x32_bf16 v[114:117], v[164:167], v[180:183], v[114:117]
	v_mfma_f32_16x16x32_bf16 v[102:105], v[144:147], v[188:191], v[102:105]
	v_mfma_f32_16x16x32_bf16 v[98:101], v[164:167], v[188:191], v[98:101]
	v_mfma_f32_16x16x32_bf16 v[86:89], v[144:147], v[196:199], v[86:89]
	v_mfma_f32_16x16x32_bf16 v[82:85], v[164:167], v[196:199], v[82:85]
	v_mfma_f32_16x16x32_bf16 v[126:129], v[160:163], v[176:179], v[126:129]
	v_mfma_f32_16x16x32_bf16 v[122:125], v[168:171], v[176:179], v[122:125]
	v_mfma_f32_16x16x32_bf16 v[118:121], v[160:163], v[184:187], v[118:121]
	v_mfma_f32_16x16x32_bf16 v[114:117], v[168:171], v[184:187], v[114:117]
	v_mfma_f32_16x16x32_bf16 v[102:105], v[160:163], v[192:195], v[102:105]
	v_mfma_f32_16x16x32_bf16 v[98:101], v[168:171], v[192:195], v[98:101]
	v_mfma_f32_16x16x32_bf16 v[86:89], v[160:163], v[200:203], v[86:89]
	v_mfma_f32_16x16x32_bf16 v[82:85], v[168:171], v[200:203], v[82:85]
.Lht_ip_mf0:
	s_setprio 0
	s_barrier
	s_add_i32 s56, 0, 0x14000
	v_add_u32_e32 v148, s56, v141
	s_add_i32 s53, s53, s28
	ds_read_b128 v[234:237], v148
	ds_read_b128 v[238:241], v148 offset:1024
	ds_read_b128 v[242:245], v148 offset:2048
	ds_read_b128 v[246:249], v148 offset:3072
	v_lshl_add_u64 v[148:149], s[22:23], 0, v[0:1]
	s_mov_b32 m0, s53
	v_lshl_add_u64 v[204:205], s[22:23], 0, v[130:131]
	global_load_lds_dwordx4 v[148:149], off
	s_add_i32 m0, s53, 0x2000
	s_nop 0
	global_load_lds_dwordx4 v[204:205], off
	s_barrier
	s_waitcnt lgkmcnt(0)
	s_setprio 1
	s_waitcnt lgkmcnt(0)
	s_cmp_eq_u32 s100, 1
	s_cbranch_scc1 .Lht_ip_mf1
	v_mfma_f32_16x16x32_bf16 v[110:113], v[234:237], v[172:175], v[110:113]
	v_mfma_f32_16x16x32_bf16 v[106:109], v[242:245], v[172:175], v[106:109]
	v_mfma_f32_16x16x32_bf16 v[94:97], v[234:237], v[180:183], v[94:97]
	v_mfma_f32_16x16x32_bf16 v[90:93], v[242:245], v[180:183], v[90:93]
	v_mfma_f32_16x16x32_bf16 v[78:81], v[234:237], v[188:191], v[78:81]
	v_mfma_f32_16x16x32_bf16 v[74:77], v[242:245], v[188:191], v[74:77]
	v_mfma_f32_16x16x32_bf16 v[70:73], v[234:237], v[196:199], v[70:73]
	v_mfma_f32_16x16x32_bf16 v[66:69], v[242:245], v[196:199], v[66:69]
	v_mfma_f32_16x16x32_bf16 v[110:113], v[238:241], v[176:179], v[110:113]
	v_mfma_f32_16x16x32_bf16 v[106:109], v[246:249], v[176:179], v[106:109]
	v_mfma_f32_16x16x32_bf16 v[94:97], v[238:241], v[184:187], v[94:97]
	v_mfma_f32_16x16x32_bf16 v[90:93], v[246:249], v[184:187], v[90:93]
	v_mfma_f32_16x16x32_bf16 v[78:81], v[238:241], v[192:195], v[78:81]
	v_mfma_f32_16x16x32_bf16 v[74:77], v[246:249], v[192:195], v[74:77]
	v_mfma_f32_16x16x32_bf16 v[70:73], v[238:241], v[200:203], v[70:73]
	v_mfma_f32_16x16x32_bf16 v[66:69], v[246:249], v[200:203], v[66:69]
.Lht_ip_mf1:
	s_setprio 0
	s_mov_b32 m0, s3
	v_lshl_add_u64 v[250:251], s[24:25], 0, v[134:135]
	s_barrier
	ds_read_b128 v[172:175], v143 offset:16384
	ds_read_b128 v[176:179], v143 offset:17408
	ds_read_b128 v[180:183], v143 offset:18432
	ds_read_b128 v[184:187], v143 offset:19456
	ds_read_b128 v[188:191], v143 offset:20480
	ds_read_b128 v[192:195], v143 offset:21504
	ds_read_b128 v[196:199], v143 offset:22528
	ds_read_b128 v[200:203], v143 offset:23552
	global_load_lds_dwordx4 v[250:251], off
	v_lshl_add_u64 v[252:253], s[24:25], 0, v[132:133]
	s_mov_b32 m0, s30
	s_nop 0
	global_load_lds_dwordx4 v[252:253], off
	s_barrier
	s_waitcnt lgkmcnt(0)
	s_setprio 1
	s_waitcnt lgkmcnt(0)
	s_cmp_eq_u32 s100, 2
	s_cbranch_scc1 .Lht_ip_mf2
	v_mfma_f32_16x16x32_bf16 v[62:65], v[144:147], v[172:175], v[62:65]
	v_mfma_f32_16x16x32_bf16 v[58:61], v[164:167], v[172:175], v[58:61]
	v_mfma_f32_16x16x32_bf16 v[54:57], v[144:147], v[180:183], v[54:57]
	v_mfma_f32_16x16x32_bf16 v[50:53], v[164:167], v[180:183], v[50:53]
	v_mfma_f32_16x16x32_bf16 v[38:41], v[144:147], v[188:191], v[38:41]
	v_mfma_f32_16x16x32_bf16 v[34:37], v[164:167], v[188:191], v[34:37]
	v_mfma_f32_16x16x32_bf16 v[22:25], v[144:147], v[196:199], v[22:25]
	v_mfma_f32_16x16x32_bf16 v[18:21], v[164:167], v[196:199], v[18:21]
	v_mfma_f32_16x16x32_bf16 v[62:65], v[160:163], v[176:179], v[62:65]
	v_mfma_f32_16x16x32_bf16 v[58:61], v[168:171], v[176:179], v[58:61]
	v_mfma_f32_16x16x32_bf16 v[54:57], v[160:163], v[184:187], v[54:57]
	v_mfma_f32_16x16x32_bf16 v[50:53], v[168:171], v[184:187], v[50:53]
	v_mfma_f32_16x16x32_bf16 v[38:41], v[160:163], v[192:195], v[38:41]
	v_mfma_f32_16x16x32_bf16 v[34:37], v[168:171], v[192:195], v[34:37]
	v_mfma_f32_16x16x32_bf16 v[22:25], v[160:163], v[200:203], v[22:25]
	v_mfma_f32_16x16x32_bf16 v[18:21], v[168:171], v[200:203], v[18:21]
.Lht_ip_mf2:
	s_setprio 0
	s_barrier
	s_add_u32 s54, s22, 0x40000
	s_addc_u32 s55, s23, 0
	s_add_i32 s53, s56, s28
	v_lshl_add_u64 v[144:145], s[54:55], 0, v[0:1]
	s_mov_b32 m0, s53
	s_nop 0
	global_load_lds_dwordx4 v[144:145], off
	v_lshl_add_u64 v[144:145], s[54:55], 0, v[130:131]
	s_add_i32 m0, s53, 0x2000
	s_nop 0
	global_load_lds_dwordx4 v[144:145], off
	s_waitcnt vmcnt(6)
	s_barrier
	s_setprio 1
	s_cmp_eq_u32 s100, 1
	s_cbranch_scc1 .Lht_ip_mf3
	v_mfma_f32_16x16x32_bf16 v[46:49], v[234:237], v[172:175], v[46:49]
	v_mfma_f32_16x16x32_bf16 v[42:45], v[242:245], v[172:175], v[42:45]
	v_mfma_f32_16x16x32_bf16 v[30:33], v[234:237], v[180:183], v[30:33]
	v_mfma_f32_16x16x32_bf16 v[26:29], v[242:245], v[180:183], v[26:29]
	v_mfma_f32_16x16x32_bf16 v[14:17], v[234:237], v[188:191], v[14:17]
	v_mfma_f32_16x16x32_bf16 v[10:13], v[242:245], v[188:191], v[10:13]
	v_mfma_f32_16x16x32_bf16 v[6:9], v[234:237], v[196:199], v[6:9]
	v_mfma_f32_16x16x32_bf16 v[2:5], v[242:245], v[196:199], v[2:5]
	v_mfma_f32_16x16x32_bf16 v[46:49], v[238:241], v[176:179], v[46:49]
	v_mfma_f32_16x16x32_bf16 v[42:45], v[246:249], v[176:179], v[42:45]
	v_mfma_f32_16x16x32_bf16 v[30:33], v[238:241], v[184:187], v[30:33]
	v_mfma_f32_16x16x32_bf16 v[26:29], v[246:249], v[184:187], v[26:29]
	v_mfma_f32_16x16x32_bf16 v[14:17], v[238:241], v[192:195], v[14:17]
	v_mfma_f32_16x16x32_bf16 v[10:13], v[246:249], v[192:195], v[10:13]
	v_mfma_f32_16x16x32_bf16 v[6:9], v[238:241], v[200:203], v[6:9]
	v_mfma_f32_16x16x32_bf16 v[2:5], v[246:249], v[200:203], v[2:5]
.Lht_ip_mf3:
	s_setprio 0
	s_add_i32 s53, 0, 0x18000
	v_add_u32_e32 v159, s53, v141
	s_barrier
	ds_read_b128 v[144:147], v159
	ds_read_b128 v[160:163], v159 offset:1024
	ds_read_b128 v[164:167], v159 offset:2048
	ds_read_b128 v[168:171], v159 offset:3072
	s_add_u32 s24, s24, 0x40000
	s_addc_u32 s25, s25, 0
	s_mov_b32 m0, s31
	v_lshl_add_u64 v[234:235], s[24:25], 0, v[134:135]
	ds_read_b128 v[172:175], v143 offset:32768
	ds_read_b128 v[176:179], v143 offset:33792
	ds_read_b128 v[180:183], v143 offset:34816
	ds_read_b128 v[184:187], v143 offset:35840
	ds_read_b128 v[188:191], v143 offset:36864
	ds_read_b128 v[192:195], v143 offset:37888
	ds_read_b128 v[196:199], v143 offset:38912
	ds_read_b128 v[200:203], v143 offset:39936
	global_load_lds_dwordx4 v[234:235], off
	v_lshl_add_u64 v[234:235], s[24:25], 0, v[132:133]
	s_mov_b32 m0, s34
	s_nop 0
	global_load_lds_dwordx4 v[234:235], off
	s_waitcnt lgkmcnt(8)
	s_barrier
	s_waitcnt lgkmcnt(0)
	s_setprio 1
	s_waitcnt lgkmcnt(0)
	s_cmp_eq_u32 s100, 2
	s_cbranch_scc1 .Lht_ip_mf4
	v_mfma_f32_16x16x32_bf16 v[126:129], v[144:147], v[172:175], v[126:129]
	v_mfma_f32_16x16x32_bf16 v[122:125], v[164:167], v[172:175], v[122:125]
	v_mfma_f32_16x16x32_bf16 v[118:121], v[144:147], v[180:183], v[118:121]
	v_mfma_f32_16x16x32_bf16 v[114:117], v[164:167], v[180:183], v[114:117]
	v_mfma_f32_16x16x32_bf16 v[102:105], v[144:147], v[188:191], v[102:105]
	v_mfma_f32_16x16x32_bf16 v[98:101], v[164:167], v[188:191], v[98:101]
	v_mfma_f32_16x16x32_bf16 v[86:89], v[144:147], v[196:199], v[86:89]
	v_mfma_f32_16x16x32_bf16 v[82:85], v[164:167], v[196:199], v[82:85]
	v_mfma_f32_16x16x32_bf16 v[126:129], v[160:163], v[176:179], v[126:129]
	v_mfma_f32_16x16x32_bf16 v[122:125], v[168:171], v[176:179], v[122:125]
	v_mfma_f32_16x16x32_bf16 v[118:121], v[160:163], v[184:187], v[118:121]
	v_mfma_f32_16x16x32_bf16 v[114:117], v[168:171], v[184:187], v[114:117]
	v_mfma_f32_16x16x32_bf16 v[102:105], v[160:163], v[192:195], v[102:105]
	v_mfma_f32_16x16x32_bf16 v[98:101], v[168:171], v[192:195], v[98:101]
	v_mfma_f32_16x16x32_bf16 v[86:89], v[160:163], v[200:203], v[86:89]
	v_mfma_f32_16x16x32_bf16 v[82:85], v[168:171], v[200:203], v[82:85]
.Lht_ip_mf4:
	s_setprio 0
	s_barrier
	s_add_i32 s24, 0, 0x1c000
	s_add_i32 s25, s53, s28
	v_add_u32_e32 v159, s24, v141
	v_lshl_add_u64 v[148:149], v[148:149], 0, s[20:21]
	s_mov_b32 m0, s25
	ds_read_b128 v[234:237], v159
	ds_read_b128 v[238:241], v159 offset:1024
	ds_read_b128 v[242:245], v159 offset:2048
	ds_read_b128 v[246:249], v159 offset:3072
	global_load_lds_dwordx4 v[148:149], off
	v_lshl_add_u64 v[148:149], v[204:205], 0, s[20:21]
	s_add_i32 m0, s25, 0x2000
	s_nop 0
	global_load_lds_dwordx4 v[148:149], off
	s_barrier
	s_waitcnt lgkmcnt(0)
	s_setprio 1
	s_waitcnt lgkmcnt(0)
	s_cmp_eq_u32 s100, 1
	s_cbranch_scc1 .Lht_ip_mf5
	v_mfma_f32_16x16x32_bf16 v[110:113], v[234:237], v[172:175], v[110:113]
	v_mfma_f32_16x16x32_bf16 v[106:109], v[242:245], v[172:175], v[106:109]
	v_mfma_f32_16x16x32_bf16 v[94:97], v[234:237], v[180:183], v[94:97]
	v_mfma_f32_16x16x32_bf16 v[90:93], v[242:245], v[180:183], v[90:93]
	v_mfma_f32_16x16x32_bf16 v[78:81], v[234:237], v[188:191], v[78:81]
	v_mfma_f32_16x16x32_bf16 v[74:77], v[242:245], v[188:191], v[74:77]
	v_mfma_f32_16x16x32_bf16 v[70:73], v[234:237], v[196:199], v[70:73]
	v_mfma_f32_16x16x32_bf16 v[66:69], v[242:245], v[196:199], v[66:69]
	v_mfma_f32_16x16x32_bf16 v[110:113], v[238:241], v[176:179], v[110:113]
	v_mfma_f32_16x16x32_bf16 v[106:109], v[246:249], v[176:179], v[106:109]
	v_mfma_f32_16x16x32_bf16 v[94:97], v[238:241], v[184:187], v[94:97]
	v_mfma_f32_16x16x32_bf16 v[90:93], v[246:249], v[184:187], v[90:93]
	v_mfma_f32_16x16x32_bf16 v[78:81], v[238:241], v[192:195], v[78:81]
	v_mfma_f32_16x16x32_bf16 v[74:77], v[246:249], v[192:195], v[74:77]
	v_mfma_f32_16x16x32_bf16 v[70:73], v[238:241], v[200:203], v[70:73]
	v_mfma_f32_16x16x32_bf16 v[66:69], v[246:249], v[200:203], v[66:69]
.Lht_ip_mf5:
	s_setprio 0
	s_mov_b32 m0, s35
	v_lshl_add_u64 v[148:149], v[250:251], 0, s[20:21]
	s_barrier
	ds_read_b128 v[172:175], v143 offset:49152
	ds_read_b128 v[176:179], v143 offset:50176
	ds_read_b128 v[180:183], v143 offset:51200
	ds_read_b128 v[184:187], v143 offset:52224
	ds_read_b128 v[188:191], v143 offset:53248
	ds_read_b128 v[192:195], v143 offset:54272
	ds_read_b128 v[196:199], v143 offset:55296
	ds_read_b128 v[200:203], v143 offset:56320
	global_load_lds_dwordx4 v[148:149], off
	v_lshl_add_u64 v[148:149], v[252:253], 0, s[20:21]
	s_mov_b32 m0, s38
	s_nop 0
	global_load_lds_dwordx4 v[148:149], off
	s_barrier
	s_waitcnt lgkmcnt(0)
	s_setprio 1
	s_waitcnt lgkmcnt(0)
	s_cmp_eq_u32 s100, 2
	s_cbranch_scc1 .Lht_ip_mf6
	v_mfma_f32_16x16x32_bf16 v[62:65], v[144:147], v[172:175], v[62:65]
	v_mfma_f32_16x16x32_bf16 v[58:61], v[164:167], v[172:175], v[58:61]
	v_mfma_f32_16x16x32_bf16 v[54:57], v[144:147], v[180:183], v[54:57]
	v_mfma_f32_16x16x32_bf16 v[50:53], v[164:167], v[180:183], v[50:53]
	v_mfma_f32_16x16x32_bf16 v[38:41], v[144:147], v[188:191], v[38:41]
	v_mfma_f32_16x16x32_bf16 v[34:37], v[164:167], v[188:191], v[34:37]
	v_mfma_f32_16x16x32_bf16 v[22:25], v[144:147], v[196:199], v[22:25]
	v_mfma_f32_16x16x32_bf16 v[18:21], v[164:167], v[196:199], v[18:21]
	v_mfma_f32_16x16x32_bf16 v[62:65], v[160:163], v[176:179], v[62:65]
	v_mfma_f32_16x16x32_bf16 v[58:61], v[168:171], v[176:179], v[58:61]
	v_mfma_f32_16x16x32_bf16 v[54:57], v[160:163], v[184:187], v[54:57]
	v_mfma_f32_16x16x32_bf16 v[50:53], v[168:171], v[184:187], v[50:53]
	v_mfma_f32_16x16x32_bf16 v[38:41], v[160:163], v[192:195], v[38:41]
	v_mfma_f32_16x16x32_bf16 v[34:37], v[168:171], v[192:195], v[34:37]
	v_mfma_f32_16x16x32_bf16 v[22:25], v[160:163], v[200:203], v[22:25]
	v_mfma_f32_16x16x32_bf16 v[18:21], v[168:171], v[200:203], v[18:21]
.Lht_ip_mf6:
	s_setprio 0
	s_barrier
	s_add_u32 s22, s22, 0x40080
	s_addc_u32 s23, s23, 0
	s_add_i32 s24, s24, s28
	v_lshl_add_u64 v[144:145], s[22:23], 0, v[0:1]
	s_mov_b32 m0, s24
	s_nop 0
	global_load_lds_dwordx4 v[144:145], off
	v_lshl_add_u64 v[144:145], s[22:23], 0, v[130:131]
	s_add_i32 m0, s24, 0x2000
	s_nop 0
	global_load_lds_dwordx4 v[144:145], off
	s_waitcnt vmcnt(6)
	s_barrier
	s_setprio 1
	s_cmp_eq_u32 s100, 1
	s_cbranch_scc1 .Lht_ip_mf7
	v_mfma_f32_16x16x32_bf16 v[46:49], v[234:237], v[172:175], v[46:49]
	v_mfma_f32_16x16x32_bf16 v[42:45], v[242:245], v[172:175], v[42:45]
	v_mfma_f32_16x16x32_bf16 v[30:33], v[234:237], v[180:183], v[30:33]
	v_mfma_f32_16x16x32_bf16 v[26:29], v[242:245], v[180:183], v[26:29]
	v_mfma_f32_16x16x32_bf16 v[14:17], v[234:237], v[188:191], v[14:17]
	v_mfma_f32_16x16x32_bf16 v[10:13], v[242:245], v[188:191], v[10:13]
	v_mfma_f32_16x16x32_bf16 v[6:9], v[234:237], v[196:199], v[6:9]
	v_mfma_f32_16x16x32_bf16 v[2:5], v[242:245], v[196:199], v[2:5]
	v_mfma_f32_16x16x32_bf16 v[46:49], v[238:241], v[176:179], v[46:49]
	v_mfma_f32_16x16x32_bf16 v[42:45], v[246:249], v[176:179], v[42:45]
	v_mfma_f32_16x16x32_bf16 v[30:33], v[238:241], v[184:187], v[30:33]
	v_mfma_f32_16x16x32_bf16 v[26:29], v[246:249], v[184:187], v[26:29]
	v_mfma_f32_16x16x32_bf16 v[14:17], v[238:241], v[192:195], v[14:17]
	v_mfma_f32_16x16x32_bf16 v[10:13], v[246:249], v[192:195], v[10:13]
	v_mfma_f32_16x16x32_bf16 v[6:9], v[238:241], v[200:203], v[6:9]
	v_mfma_f32_16x16x32_bf16 v[2:5], v[246:249], v[200:203], v[2:5]
.Lht_ip_mf7:
	s_setprio 0
	s_add_i32 s52, s52, 2
	s_add_u32 s50, s50, 0x100
	s_addc_u32 s51, s51, 0
	s_add_u32 s18, s18, 0x100
	s_addc_u32 s19, s19, 0
	s_cmp_gt_u32 s52, 13
	s_barrier
	s_cbranch_scc0 .LBB0_672
	v_lshl_or_b32 v144, s43, 8, v142
	v_lshl_add_u32 v148, s2, 8, v140
	v_ashrrev_i32_e32 v145, 31, v144
	v_lshl_add_u64 v[144:145], v[144:145], 1, s[46:47]
	v_cvt_pk_bf16_f32 v70, v70, v71
	v_cvt_pk_bf16_f32 v71, v72, v73
	v_cvt_pk_bf16_f32 v72, v66, v67
	v_add_u32_e32 v66, 0x80, v148
	v_mad_i64_i32 v[146:147], s[18:19], v148, s74, v[144:145]
	v_cvt_pk_bf16_f32 v110, v110, v111
	v_cvt_pk_bf16_f32 v111, v112, v113
	v_cvt_pk_bf16_f32 v112, v106, v107
	v_cvt_pk_bf16_f32 v113, v108, v109
	v_or_b32_e32 v106, 16, v148
	v_mad_i64_i32 v[66:67], s[18:19], v66, s74, v[144:145]
	v_cvt_pk_bf16_f32 v46, v46, v47
	v_cvt_pk_bf16_f32 v47, v48, v49
	v_cvt_pk_bf16_f32 v48, v42, v43
	v_cvt_pk_bf16_f32 v49, v44, v45
	v_add_u32_e32 v42, 0x90, v148
	s_cmp_eq_u32 s100, 1
	s_cbranch_scc1 .Lht_ip_st0
	global_store_dwordx4 v[146:147], v[110:113], off offset:256
.Lht_ip_st0:
	v_cvt_pk_bf16_f32 v94, v94, v95
	v_cvt_pk_bf16_f32 v95, v96, v97
	v_mad_i64_i32 v[110:111], s[18:19], v106, s74, v[144:145]
	v_cvt_pk_bf16_f32 v96, v90, v91
	v_cvt_pk_bf16_f32 v97, v92, v93
	v_or_b32_e32 v90, 32, v148
	s_cmp_eq_u32 s100, 1
	s_cbranch_scc1 .Lht_ip_st1
	global_store_dwordx4 v[66:67], v[46:49], off offset:256
.Lht_ip_st1:
	v_cvt_pk_bf16_f32 v30, v30, v31
	v_cvt_pk_bf16_f32 v31, v32, v33
	v_mad_i64_i32 v[46:47], s[18:19], v42, s74, v[144:145]
	v_cvt_pk_bf16_f32 v32, v26, v27
	v_cvt_pk_bf16_f32 v33, v28, v29
	v_add_u32_e32 v26, 0xa0, v148
	s_cmp_eq_u32 s100, 1
	s_cbranch_scc1 .Lht_ip_st2
	global_store_dwordx4 v[110:111], v[94:97], off offset:256
.Lht_ip_st2:
	v_cvt_pk_bf16_f32 v78, v78, v79
	v_cvt_pk_bf16_f32 v79, v80, v81
	v_mad_i64_i32 v[94:95], s[18:19], v90, s74, v[144:145]
	v_cvt_pk_bf16_f32 v80, v74, v75
	v_cvt_pk_bf16_f32 v81, v76, v77
	v_or_b32_e32 v74, 48, v148
	s_cmp_eq_u32 s100, 1
	s_cbranch_scc1 .Lht_ip_st3
	global_store_dwordx4 v[46:47], v[30:33], off offset:256
.Lht_ip_st3:
	v_cvt_pk_bf16_f32 v14, v14, v15
	v_cvt_pk_bf16_f32 v15, v16, v17
	v_mad_i64_i32 v[30:31], s[18:19], v26, s74, v[144:145]
	v_cvt_pk_bf16_f32 v16, v10, v11
	v_cvt_pk_bf16_f32 v17, v12, v13
	v_add_u32_e32 v10, 0xb0, v148
	s_cmp_eq_u32 s100, 1
	s_cbranch_scc1 .Lht_ip_st4
	global_store_dwordx4 v[94:95], v[78:81], off offset:256
.Lht_ip_st4:
	s_cmp_eq_u32 s100, 1
	s_cbranch_scc1 .Lht_ip_st5
	global_store_dwordx4 v[30:31], v[14:17], off offset:256
.Lht_ip_st5:
	v_cvt_pk_bf16_f32 v126, v126, v127
	v_mad_i64_i32 v[78:79], s[18:19], v74, s74, v[144:145]
	v_mad_i64_i32 v[14:15], s[18:19], v10, s74, v[144:145]
	v_cvt_pk_bf16_f32 v127, v128, v129
	v_cvt_pk_bf16_f32 v128, v122, v123
	v_cvt_pk_bf16_f32 v129, v124, v125
	v_cvt_pk_bf16_f32 v106, v118, v119
	v_cvt_pk_bf16_f32 v107, v120, v121
	v_cvt_pk_bf16_f32 v108, v114, v115
	v_cvt_pk_bf16_f32 v109, v116, v117
	v_cvt_pk_bf16_f32 v90, v102, v103
	v_cvt_pk_bf16_f32 v91, v104, v105
	v_cvt_pk_bf16_f32 v92, v98, v99
	v_cvt_pk_bf16_f32 v93, v100, v101
	v_cvt_pk_bf16_f32 v74, v86, v87
	v_cvt_pk_bf16_f32 v75, v88, v89
	v_cvt_pk_bf16_f32 v76, v82, v83
	v_cvt_pk_bf16_f32 v77, v84, v85
	v_cvt_pk_bf16_f32 v73, v68, v69
	v_cvt_pk_bf16_f32 v62, v62, v63
	v_cvt_pk_bf16_f32 v63, v64, v65
	v_cvt_pk_bf16_f32 v64, v58, v59
	v_cvt_pk_bf16_f32 v65, v60, v61
	v_cvt_pk_bf16_f32 v42, v54, v55
	v_cvt_pk_bf16_f32 v43, v56, v57
	v_cvt_pk_bf16_f32 v44, v50, v51
	v_cvt_pk_bf16_f32 v45, v52, v53
	v_cvt_pk_bf16_f32 v26, v38, v39
	v_cvt_pk_bf16_f32 v27, v40, v41
	v_cvt_pk_bf16_f32 v28, v34, v35
	v_cvt_pk_bf16_f32 v29, v36, v37
	v_cvt_pk_bf16_f32 v10, v22, v23
	v_cvt_pk_bf16_f32 v11, v24, v25
	v_cvt_pk_bf16_f32 v12, v18, v19
	v_cvt_pk_bf16_f32 v13, v20, v21
	v_cvt_pk_bf16_f32 v6, v6, v7
	v_cvt_pk_bf16_f32 v7, v8, v9
	v_cvt_pk_bf16_f32 v8, v2, v3
	v_cvt_pk_bf16_f32 v9, v4, v5
	s_and_b64 vcc, exec, s[40:41]
	s_mov_b32 s43, s8
	s_mov_b32 s2, s10
	s_mov_b64 s[18:19], s[14:15]
	s_mov_b64 s[22:23], s[12:13]
	s_cmp_eq_u32 s100, 2
	s_cbranch_scc1 .Lht_ip_st6
	global_store_dwordx4 v[146:147], v[126:129], off
.Lht_ip_st6:
	s_cmp_eq_u32 s100, 2
	s_cbranch_scc1 .Lht_ip_st7
	global_store_dwordx4 v[110:111], v[106:109], off
.Lht_ip_st7:
	s_cmp_eq_u32 s100, 2
	s_cbranch_scc1 .Lht_ip_st8
	global_store_dwordx4 v[94:95], v[90:93], off
.Lht_ip_st8:
	s_cmp_eq_u32 s100, 2
	s_cbranch_scc1 .Lht_ip_st9
	global_store_dwordx4 v[78:79], v[74:77], off
.Lht_ip_st9:
	s_cmp_eq_u32 s100, 1
	s_cbranch_scc1 .Lht_ip_st10
	global_store_dwordx4 v[78:79], v[70:73], off offset:256
.Lht_ip_st10:
	s_cmp_eq_u32 s100, 2
	s_cbranch_scc1 .Lht_ip_st11
	global_store_dwordx4 v[66:67], v[62:65], off
.Lht_ip_st11:
	s_cmp_eq_u32 s100, 2
	s_cbranch_scc1 .Lht_ip_st12
	global_store_dwordx4 v[46:47], v[42:45], off
.Lht_ip_st12:
	s_cmp_eq_u32 s100, 2
	s_cbranch_scc1 .Lht_ip_st13
	global_store_dwordx4 v[30:31], v[26:29], off
.Lht_ip_st13:
	s_cmp_eq_u32 s100, 2
	s_cbranch_scc1 .Lht_ip_st14
	global_store_dwordx4 v[14:15], v[10:13], off
.Lht_ip_st14:
	s_cmp_eq_u32 s100, 1
	s_cbranch_scc1 .Lht_ip_st15
	global_store_dwordx4 v[14:15], v[6:9], off offset:256
.Lht_ip_st15:
	s_cbranch_vccz .LBB0_669
	s_waitcnt vmcnt(0)
	s_cmpk_gt_u32 s1, 0xff
	s_cbranch_scc1 .LBB0_676
	s_barrier
